# top-k: units with at most 16 valid blocks take them all without the radix search
# baseline (speedup 1.0000x reference)
; DI void nsa_unit(LAS char* lds, int b, int g, int qb, const bf16* Z, const bf16* KC, const bf16* VC, bf16* On, int tid, int lane, int wave) {
;     ...
;         for (int qi = 0; qi < 8; ++qi) {
;             const int q = wave * 8 + qi;
;             float v = -INFINITY;
;             if (n <= qb) {
;                 v = ((impH[(0 * 64 + q) * 64 + n] + impH[(1 * 64 + q) * 64 + n]) + impH[(2 * 64 + q) * 64 + n]) + impH[(3 * 64 + q) * 64 + n];
;                 if (n == 0 || n == qb || n == qb - 1) v = 1e6f;
.LBB0_1084:
	s_add_i32 s30, s29, s65
	s_cmp_lt_u32 s68, 16
	s_cbranch_scc1 .Ltk_all
	v_mov_b32_e32 v0, 0xff800000
	v_mov_b32_e32 v37, 0xff800000
	s_and_saveexec_b64 s[18:19], s[16:17]
	s_cbranch_execz .Ltk_vals
	s_lshl_b32 s20, s30, 8
	s_add_i32 s21, s20, 0xc000
	v_add_u32_e32 v0, s20, v220
	v_add_u32_e32 v36, s21, v220
	ds_read2st64_b32 v[34:35], v36 offset0:64 offset1:128
	ds_read_b32 v0, v0 offset:49152
	ds_read_b32 v36, v36 offset:49152
	s_add_i32 s20, s20, 0x100
	s_add_i32 s21, s21, 0x100
	v_add_u32_e32 v37, s20, v220
	v_add_u32_e32 v229, s21, v220
	ds_read2st64_b32 v[38:39], v229 offset0:64 offset1:128
	ds_read_b32 v37, v37 offset:49152
	ds_read_b32 v229, v229 offset:49152
	s_waitcnt lgkmcnt(4)
	v_add_f32_e32 v0, v0, v34
	v_add_f32_e32 v0, v0, v35
	s_waitcnt lgkmcnt(3)
	v_add_f32_e32 v0, v0, v36
	s_waitcnt lgkmcnt(1)
	v_add_f32_e32 v37, v37, v38
	v_add_f32_e32 v37, v37, v39
	s_waitcnt lgkmcnt(0)
	v_add_f32_e32 v37, v37, v229
	v_mov_b32_e32 v34, 0x49742400
	v_cndmask_b32_e64 v0, v0, v34, s[12:13]
	v_cndmask_b32_e64 v37, v37, v34, s[12:13]

; DI void nsa_unit(LAS char* lds, int b, int g, int qb, const bf16* Z, const bf16* KC, const bf16* VC, bf16* On, int tid, int lane, int wave) {
;     ...
;             const bool sel = (cnt < 16) && (n <= qb);
;             const unsigned long long mk = __ballot(sel);
;             if (lane == 0) selm[q] = mk;
;         }
.Ltk_write:
	s_and_saveexec_b64 s[18:19], s[40:41]
	s_cbranch_execz .Ltk_latch
	s_lshl_b32 s30, s30, 3
	s_add_i32 s30, s30, 0x1c000
	v_mov_b32_e32 v0, s30
	v_mov_b64_e32 v[34:35], s[20:21]
	v_mov_b64_e32 v[38:39], s[100:101]
	ds_write_b64 v0, v[34:35]
	ds_write_b64 v0, v[38:39] offset:8
.Ltk_latch:
	s_or_b64 exec, exec, s[18:19]
	s_add_i32 s29, s29, 2
	s_cmp_eq_u32 s29, 8
	s_cbranch_scc0 .LBB0_1084
	s_branch .LBB0_1090
.Ltk_all:
	s_mov_b64 s[20:21], s[16:17]
	s_mov_b64 s[100:101], s[16:17]
	s_branch .Ltk_write
